# grid barrier: overall-last CU releases all XCD generation words directly (TOPGEN hop removed); XCD leaders poll their XCD word
# speedup vs baseline: 1.0003x; 1.0003x over previous
; __device__ __forceinline__ unsigned xb_ld(unsigned* p)              { return __hip_atomic_load(p, __ATOMIC_RELAXED, __HIP_MEMORY_SCOPE_AGENT); }
; __device__ __forceinline__ unsigned xb_add(unsigned* p, unsigned v) { return __hip_atomic_fetch_add(p, v, __ATOMIC_RELAXED, __HIP_MEMORY_SCOPE_AGENT); }
; #define XB_SPIN(cond, bar) do { unsigned _sp = 0; while (cond) { __builtin_amdgcn_s_sleep(1); \
;     if ((++_sp & 255u) == 0u) { if (xb_ld(&(bar)[XB_TMO])) break; if (_sp > XB_SPIN_CAP) { atomicAdd(&(bar)[XB_TMO], 1u); break; } } } } while (0)
; __device__ __forceinline__ void xcd_barrier(const XcdBarrier& b) {
;     ...
;         const unsigned old = xb_add(&bar[XB_XSUB(b.x)], 1u);
;         const unsigned gen = old / nloc;
;         if (old + 1u == (gen + 1u) * nloc) {
;             __builtin_amdgcn_fence(__ATOMIC_RELEASE, "agent");
;             asm volatile("s_waitcnt vmcnt(0)" ::: "memory");
;             const unsigned og = xb_add(&bar[XB_TOP], 1u);
;             const unsigned tg = og / nx;
;             if (og + 1u == (tg + 1u) * nx) xb_add(&bar[XB_TOPGEN], 1u);
;             else XB_SPIN(xb_ld(&bar[XB_TOPGEN]) == tg, bar);
;             __builtin_amdgcn_fence(__ATOMIC_ACQUIRE, "agent");
;             xb_add(&bar[XB_XGEN(b.x)], 1u);
;             asm volatile("s_waitcnt vmcnt(0)" ::: "memory");
;         } else {
;             XB_SPIN(xb_ld(&bar[XB_XGEN(b.x)]) == gen, bar);
.LBB0_93:
	s_or_b64 exec, exec, s[18:19]
	v_cvt_f32_u32_e32 v4, v2
	s_waitcnt vmcnt(0)
	v_readfirstlane_b32 s2, v3
	v_sub_u32_e32 v3, 0, v2
	v_rcp_iflag_f32_e32 v4, v4
	v_add_u32_e32 v5, s2, v1
	v_mul_f32_e32 v4, 0x4f7ffffe, v4
	v_cvt_u32_f32_e32 v4, v4
	v_mul_lo_u32 v1, v3, v4
	v_mul_hi_u32 v1, v4, v1
	v_add_u32_e32 v1, v4, v1
	v_mul_hi_u32 v1, v5, v1
	v_mul_lo_u32 v3, v1, v2
	v_sub_u32_e32 v3, v5, v3
	v_add_u32_e32 v4, 1, v1
	v_cmp_ge_u32_e32 vcc, v3, v2
	s_nop 1
	v_cndmask_b32_e32 v1, v1, v4, vcc
	v_sub_u32_e32 v4, v3, v2
	v_cndmask_b32_e32 v3, v3, v4, vcc
	v_add_u32_e32 v4, 1, v1
	v_cmp_ge_u32_e32 vcc, v3, v2
	v_add_u32_e32 v3, 1, v5
	s_nop 0
	v_cndmask_b32_e32 v1, v1, v4, vcc
	v_mul_lo_u32 v4, v2, v1
	v_add_u32_e32 v2, v4, v2
	v_cmp_ne_u32_e32 vcc, v3, v2
	v_mov_b32_e32 v17, v1
	s_and_saveexec_b64 s[2:3], vcc
	s_xor_b64 s[14:15], exec, s[2:3]
	s_cbranch_execz .LBB0_107
	s_waitcnt lgkmcnt(0)
	v_mov_b32_e32 v0, 0x2000
	global_load_dword v0, v0, s[8:9] offset:1024 sc1
	s_add_u32 s22, s8, 0x2400
	s_addc_u32 s23, s9, 0
	s_waitcnt vmcnt(0)
	v_cmp_eq_u32_e32 vcc, v0, v1
	s_and_saveexec_b64 s[18:19], vcc
	s_cbranch_execz .LBB0_106
	s_add_u32 s20, s6, 0x4200
	s_addc_u32 s21, s7, 0
	s_mov_b32 s2, 1
	s_mov_b64 s[24:25], 0
	v_mov_b32_e32 v0, 0
	s_branch .LBB0_97

; __device__ __forceinline__ unsigned xb_ld(unsigned* p)              { return __hip_atomic_load(p, __ATOMIC_RELAXED, __HIP_MEMORY_SCOPE_AGENT); }
; __device__ __forceinline__ unsigned xb_add(unsigned* p, unsigned v) { return __hip_atomic_fetch_add(p, v, __ATOMIC_RELAXED, __HIP_MEMORY_SCOPE_AGENT); }
; #define XB_SPIN(cond, bar) do { unsigned _sp = 0; while (cond) { __builtin_amdgcn_s_sleep(1); \
;     if ((++_sp & 255u) == 0u) { if (xb_ld(&(bar)[XB_TMO])) break; if (_sp > XB_SPIN_CAP) { atomicAdd(&(bar)[XB_TMO], 1u); break; } } } } while (0)
; __device__ __forceinline__ void xcd_barrier(const XcdBarrier& b) {
;     ...
;             const unsigned og = xb_add(&bar[XB_TOP], 1u);
;             const unsigned tg = og / nx;
;             if (og + 1u == (tg + 1u) * nx) xb_add(&bar[XB_TOPGEN], 1u);
;             else XB_SPIN(xb_ld(&bar[XB_TOPGEN]) == tg, bar);
.LBB0_110:
	s_or_b64 exec, exec, s[18:19]
	v_cvt_f32_u32_e32 v3, v0
	s_waitcnt vmcnt(0)
	v_readfirstlane_b32 s2, v2
	s_add_u32 s18, s8, 0x2400
	s_addc_u32 s19, s9, 0
	v_rcp_iflag_f32_e32 v3, v3
	v_add_u32_e32 v1, s2, v1
	v_add_u32_e32 v4, 1, v1
	s_mov_b64 s[20:21], -1
	v_mul_f32_e32 v2, 0x4f7ffffe, v3
	v_cvt_u32_f32_e32 v2, v2
	v_sub_u32_e32 v3, 0, v0
	v_mul_lo_u32 v3, v3, v2
	v_mul_hi_u32 v3, v2, v3
	v_add_u32_e32 v2, v2, v3
	v_mul_hi_u32 v2, v1, v2
	v_mul_lo_u32 v3, v2, v0
	v_sub_u32_e32 v1, v1, v3
	v_add_u32_e32 v5, 1, v2
	v_cmp_ge_u32_e32 vcc, v1, v0
	v_sub_u32_e32 v3, v1, v0
	s_nop 0
	v_cndmask_b32_e32 v2, v2, v5, vcc
	v_cndmask_b32_e32 v1, v1, v3, vcc
	v_add_u32_e32 v3, 1, v2
	v_cmp_ge_u32_e32 vcc, v1, v0
	s_nop 1
	v_cndmask_b32_e32 v2, v2, v3, vcc
	v_mul_lo_u32 v1, v0, v2
	v_add_u32_e32 v0, v1, v0
	v_cmp_ne_u32_e32 vcc, v4, v0
	v_mov_b64_e32 v[0:1], s[18:19]
	s_and_saveexec_b64 s[14:15], vcc
	s_cbranch_execz .Lxb0_last
	v_mov_b32_e32 v0, 0
	global_load_dword v1, v0, s[18:19] sc1
	s_mov_b64 s[24:25], 0
	s_waitcnt vmcnt(0)
	v_cmp_eq_u32_e32 vcc, v1, v17
	s_and_saveexec_b64 s[22:23], vcc
	s_cbranch_execz .LBB0_121
	s_add_u32 s20, s6, 0x4200
	s_addc_u32 s21, s7, 0
	s_mov_b32 s2, 1
	s_mov_b64 s[6:7], 0
	s_branch .LBB0_114

; __device__ __forceinline__ unsigned xb_ld(unsigned* p)              { return __hip_atomic_load(p, __ATOMIC_RELAXED, __HIP_MEMORY_SCOPE_AGENT); }
; __device__ __forceinline__ unsigned xb_add(unsigned* p, unsigned v) { return __hip_atomic_fetch_add(p, v, __ATOMIC_RELAXED, __HIP_MEMORY_SCOPE_AGENT); }
; #define XB_SPIN(cond, bar) do { unsigned _sp = 0; while (cond) { __builtin_amdgcn_s_sleep(1); \
;     if ((++_sp & 255u) == 0u) { if (xb_ld(&(bar)[XB_TMO])) break; if (_sp > XB_SPIN_CAP) { atomicAdd(&(bar)[XB_TMO], 1u); break; } } } } while (0)
; __device__ __forceinline__ void xcd_barrier(const XcdBarrier& b) {
;     ...
;             if (og + 1u == (tg + 1u) * nx) xb_add(&bar[XB_TOPGEN], 1u);
;             else XB_SPIN(xb_ld(&bar[XB_TOPGEN]) == tg, bar);
.LBB0_116:
	global_load_dword v1, v0, s[18:19] sc1
	s_add_i32 s2, s2, 1
	s_mov_b64 s[26:27], -1
	s_waitcnt vmcnt(0)
	v_cmp_ne_u32_e32 vcc, v1, v17
	s_orn2_b64 s[30:31], vcc, exec
	s_branch .LBB0_113

; __device__ __forceinline__ unsigned xb_ld(unsigned* p)              { return __hip_atomic_load(p, __ATOMIC_RELAXED, __HIP_MEMORY_SCOPE_AGENT); }
; __device__ __forceinline__ unsigned xb_add(unsigned* p, unsigned v) { return __hip_atomic_fetch_add(p, v, __ATOMIC_RELAXED, __HIP_MEMORY_SCOPE_AGENT); }
; #define XB_SPIN(cond, bar) do { unsigned _sp = 0; while (cond) { __builtin_amdgcn_s_sleep(1); \
;     if ((++_sp & 255u) == 0u) { if (xb_ld(&(bar)[XB_TMO])) break; if (_sp > XB_SPIN_CAP) { atomicAdd(&(bar)[XB_TMO], 1u); break; } } } } while (0)
; __device__ __forceinline__ void xcd_barrier(const XcdBarrier& b) {
;     ...
;             const unsigned og = xb_add(&bar[XB_TOP], 1u);
;             const unsigned tg = og / nx;
;             if (og + 1u == (tg + 1u) * nx) xb_add(&bar[XB_TOPGEN], 1u);
;             else XB_SPIN(xb_ld(&bar[XB_TOPGEN]) == tg, bar);
;             __builtin_amdgcn_fence(__ATOMIC_ACQUIRE, "agent");
;             xb_add(&bar[XB_XGEN(b.x)], 1u);
.LBB0_121:
	s_or_b64 exec, exec, s[22:23]
	v_mov_b64_e32 v[0:1], s[20:21]
	s_orn2_b64 s[20:21], s[24:25], exec
	s_branch .LBB0_122
.Lxb0_last:
	s_mov_b64 exec, 0xffff
	v_mbcnt_lo_u32_b32 v2, -1, 0
	v_lshlrev_b32_e32 v2, 8, v2
	v_add_u32_e32 v2, 0x6400, v2
	v_mov_b32_e32 v3, 1
	global_atomic_add v2, v3, s[6:7]
	s_mov_b64 exec, 0
	s_mov_b64 s[20:21], 0

; __device__ __forceinline__ unsigned xb_add(unsigned* p, unsigned v) { return __hip_atomic_fetch_add(p, v, __ATOMIC_RELAXED, __HIP_MEMORY_SCOPE_AGENT); }
; __device__ __forceinline__ void xcd_barrier(const XcdBarrier& b) {
;     ...
;             __builtin_amdgcn_fence(__ATOMIC_ACQUIRE, "agent");
;             xb_add(&bar[XB_XGEN(b.x)], 1u);
;             asm volatile("s_waitcnt vmcnt(0)" ::: "memory");
.LBB0_124:
	s_or_b64 exec, exec, s[6:7]
	s_mov_b64 s[6:7], exec
	v_mbcnt_lo_u32_b32 v0, s6, 0
	v_mbcnt_hi_u32_b32 v0, s7, v0
	v_cmp_eq_u32_e32 vcc, 0, v0
	s_waitcnt vmcnt(0)
	buffer_inv sc1
	s_and_saveexec_b64 s[14:15], vcc
	s_cbranch_execz .LBB0_126
	s_bcnt1_i32_b64 s2, s[6:7]
	v_mov_b32_e32 v0, 0x2000
	v_mov_b32_e32 v1, s2
.LBB0_126:
	s_or_b64 exec, exec, s[14:15]
	s_waitcnt vmcnt(0)

; __device__ __forceinline__ unsigned xb_ld(unsigned* p)              { return __hip_atomic_load(p, __ATOMIC_RELAXED, __HIP_MEMORY_SCOPE_AGENT); }
; __device__ __forceinline__ unsigned xb_add(unsigned* p, unsigned v) { return __hip_atomic_fetch_add(p, v, __ATOMIC_RELAXED, __HIP_MEMORY_SCOPE_AGENT); }
; #define XB_SPIN(cond, bar) do { unsigned _sp = 0; while (cond) { __builtin_amdgcn_s_sleep(1); \
;     if ((++_sp & 255u) == 0u) { if (xb_ld(&(bar)[XB_TMO])) break; if (_sp > XB_SPIN_CAP) { atomicAdd(&(bar)[XB_TMO], 1u); break; } } } } while (0)
; __device__ __forceinline__ void xcd_barrier(const XcdBarrier& b) {
;     ...
;         const unsigned old = xb_add(&bar[XB_XSUB(b.x)], 1u);
;         const unsigned gen = old / nloc;
;         if (old + 1u == (gen + 1u) * nloc) {
;             __builtin_amdgcn_fence(__ATOMIC_RELEASE, "agent");
;             asm volatile("s_waitcnt vmcnt(0)" ::: "memory");
;             const unsigned og = xb_add(&bar[XB_TOP], 1u);
;             const unsigned tg = og / nx;
;             if (og + 1u == (tg + 1u) * nx) xb_add(&bar[XB_TOPGEN], 1u);
;             else XB_SPIN(xb_ld(&bar[XB_TOPGEN]) == tg, bar);
;             __builtin_amdgcn_fence(__ATOMIC_ACQUIRE, "agent");
;             xb_add(&bar[XB_XGEN(b.x)], 1u);
;             asm volatile("s_waitcnt vmcnt(0)" ::: "memory");
;         } else {
;             XB_SPIN(xb_ld(&bar[XB_XGEN(b.x)]) == gen, bar);
.LBB0_368:
	s_or_b64 exec, exec, s[14:15]
	v_cvt_f32_u32_e32 v5, v3
	s_waitcnt vmcnt(0)
	v_readfirstlane_b32 s2, v4
	v_sub_u32_e32 v4, 0, v3
	v_rcp_iflag_f32_e32 v5, v5
	v_add_u32_e32 v6, s2, v2
	v_mul_f32_e32 v5, 0x4f7ffffe, v5
	v_cvt_u32_f32_e32 v5, v5
	v_mul_lo_u32 v2, v4, v5
	v_mul_hi_u32 v2, v5, v2
	v_add_u32_e32 v2, v5, v2
	v_mul_hi_u32 v2, v6, v2
	v_mul_lo_u32 v4, v2, v3
	v_sub_u32_e32 v4, v6, v4
	v_add_u32_e32 v5, 1, v2
	v_cmp_ge_u32_e32 vcc, v4, v3
	s_nop 1
	v_cndmask_b32_e32 v2, v2, v5, vcc
	v_sub_u32_e32 v5, v4, v3
	v_cndmask_b32_e32 v4, v4, v5, vcc
	v_add_u32_e32 v5, 1, v2
	v_cmp_ge_u32_e32 vcc, v4, v3
	v_add_u32_e32 v4, 1, v6
	s_nop 0
	v_cndmask_b32_e32 v2, v2, v5, vcc
	v_mul_lo_u32 v5, v3, v2
	v_add_u32_e32 v3, v5, v3
	v_cmp_ne_u32_e32 vcc, v4, v3
	v_mov_b32_e32 v17, v2
	s_and_saveexec_b64 s[12:13], vcc
	s_xor_b64 s[12:13], exec, s[12:13]
	s_cbranch_execz .LBB0_382
	s_waitcnt lgkmcnt(0)
	v_mov_b32_e32 v0, 0x2000
	global_load_dword v0, v0, s[8:9] offset:1024 sc1
	s_add_u32 s40, s8, 0x2400
	s_addc_u32 s41, s9, 0
	s_waitcnt vmcnt(0)
	v_cmp_eq_u32_e32 vcc, v0, v2
	s_and_saveexec_b64 s[14:15], vcc
	s_cbranch_execz .LBB0_381
	s_add_u32 s38, s6, 0x4200
	s_addc_u32 s39, s7, 0
	s_mov_b32 s2, 1
	s_mov_b64 s[42:43], 0
	s_branch .LBB0_372

; __device__ __forceinline__ unsigned xb_ld(unsigned* p)              { return __hip_atomic_load(p, __ATOMIC_RELAXED, __HIP_MEMORY_SCOPE_AGENT); }
; __device__ __forceinline__ unsigned xb_add(unsigned* p, unsigned v) { return __hip_atomic_fetch_add(p, v, __ATOMIC_RELAXED, __HIP_MEMORY_SCOPE_AGENT); }
; #define XB_SPIN(cond, bar) do { unsigned _sp = 0; while (cond) { __builtin_amdgcn_s_sleep(1); \
;     if ((++_sp & 255u) == 0u) { if (xb_ld(&(bar)[XB_TMO])) break; if (_sp > XB_SPIN_CAP) { atomicAdd(&(bar)[XB_TMO], 1u); break; } } } } while (0)
; __device__ __forceinline__ void xcd_barrier(const XcdBarrier& b) {
;     ...
;             const unsigned og = xb_add(&bar[XB_TOP], 1u);
;             const unsigned tg = og / nx;
;             if (og + 1u == (tg + 1u) * nx) xb_add(&bar[XB_TOPGEN], 1u);
;             else XB_SPIN(xb_ld(&bar[XB_TOPGEN]) == tg, bar);
.LBB0_385:
	s_or_b64 exec, exec, s[14:15]
	v_cvt_f32_u32_e32 v4, v0
	s_waitcnt vmcnt(0)
	v_readfirstlane_b32 s2, v3
	s_add_u32 s14, s8, 0x2400
	s_addc_u32 s15, s9, 0
	v_rcp_iflag_f32_e32 v4, v4
	v_add_u32_e32 v2, s2, v2
	v_add_u32_e32 v5, 1, v2
	s_mov_b64 s[38:39], -1
	v_mul_f32_e32 v3, 0x4f7ffffe, v4
	v_cvt_u32_f32_e32 v3, v3
	v_sub_u32_e32 v4, 0, v0
	v_mul_lo_u32 v4, v4, v3
	v_mul_hi_u32 v4, v3, v4
	v_add_u32_e32 v3, v3, v4
	v_mul_hi_u32 v3, v2, v3
	v_mul_lo_u32 v4, v3, v0
	v_sub_u32_e32 v2, v2, v4
	v_add_u32_e32 v6, 1, v3
	v_cmp_ge_u32_e32 vcc, v2, v0
	v_sub_u32_e32 v4, v2, v0
	s_nop 0
	v_cndmask_b32_e32 v3, v3, v6, vcc
	v_cndmask_b32_e32 v2, v2, v4, vcc
	v_add_u32_e32 v4, 1, v3
	v_cmp_ge_u32_e32 vcc, v2, v0
	s_nop 1
	v_cndmask_b32_e32 v4, v3, v4, vcc
	v_mul_lo_u32 v2, v0, v4
	v_add_u32_e32 v0, v2, v0
	v_cmp_ne_u32_e32 vcc, v5, v0
	v_mov_b64_e32 v[2:3], s[14:15]
	s_and_saveexec_b64 s[12:13], vcc
	s_cbranch_execz .Lxb1_last
	global_load_dword v0, v1, s[14:15] sc1
	s_mov_b64 s[42:43], 0
	s_waitcnt vmcnt(0)
	v_cmp_eq_u32_e32 vcc, v0, v17
	s_and_saveexec_b64 s[40:41], vcc
	s_cbranch_execz .LBB0_396
	s_add_u32 s38, s6, 0x4200
	s_addc_u32 s39, s7, 0
	s_mov_b32 s2, 1
	s_mov_b64 s[6:7], 0
	s_branch .LBB0_389

; __device__ __forceinline__ unsigned xb_ld(unsigned* p)              { return __hip_atomic_load(p, __ATOMIC_RELAXED, __HIP_MEMORY_SCOPE_AGENT); }
; __device__ __forceinline__ unsigned xb_add(unsigned* p, unsigned v) { return __hip_atomic_fetch_add(p, v, __ATOMIC_RELAXED, __HIP_MEMORY_SCOPE_AGENT); }
; #define XB_SPIN(cond, bar) do { unsigned _sp = 0; while (cond) { __builtin_amdgcn_s_sleep(1); \
;     if ((++_sp & 255u) == 0u) { if (xb_ld(&(bar)[XB_TMO])) break; if (_sp > XB_SPIN_CAP) { atomicAdd(&(bar)[XB_TMO], 1u); break; } } } } while (0)
; __device__ __forceinline__ void xcd_barrier(const XcdBarrier& b) {
;     ...
;             if (og + 1u == (tg + 1u) * nx) xb_add(&bar[XB_TOPGEN], 1u);
;             else XB_SPIN(xb_ld(&bar[XB_TOPGEN]) == tg, bar);
.LBB0_391:
	global_load_dword v0, v1, s[14:15] sc1
	s_add_i32 s2, s2, 1
	s_mov_b64 s[46:47], -1
	s_waitcnt vmcnt(0)
	v_cmp_ne_u32_e32 vcc, v0, v17
	s_orn2_b64 s[44:45], vcc, exec
	s_branch .LBB0_388

; __device__ __forceinline__ unsigned xb_ld(unsigned* p)              { return __hip_atomic_load(p, __ATOMIC_RELAXED, __HIP_MEMORY_SCOPE_AGENT); }
; __device__ __forceinline__ unsigned xb_add(unsigned* p, unsigned v) { return __hip_atomic_fetch_add(p, v, __ATOMIC_RELAXED, __HIP_MEMORY_SCOPE_AGENT); }
; #define XB_SPIN(cond, bar) do { unsigned _sp = 0; while (cond) { __builtin_amdgcn_s_sleep(1); \
;     if ((++_sp & 255u) == 0u) { if (xb_ld(&(bar)[XB_TMO])) break; if (_sp > XB_SPIN_CAP) { atomicAdd(&(bar)[XB_TMO], 1u); break; } } } } while (0)
; __device__ __forceinline__ void xcd_barrier(const XcdBarrier& b) {
;     ...
;             const unsigned og = xb_add(&bar[XB_TOP], 1u);
;             const unsigned tg = og / nx;
;             if (og + 1u == (tg + 1u) * nx) xb_add(&bar[XB_TOPGEN], 1u);
;             else XB_SPIN(xb_ld(&bar[XB_TOPGEN]) == tg, bar);
;             __builtin_amdgcn_fence(__ATOMIC_ACQUIRE, "agent");
;             xb_add(&bar[XB_XGEN(b.x)], 1u);
.LBB0_396:
	s_or_b64 exec, exec, s[40:41]
	v_mov_b64_e32 v[2:3], s[38:39]
	s_orn2_b64 s[38:39], s[42:43], exec
	s_branch .LBB0_397
.Lxb1_last:
	s_mov_b64 exec, 0xffff
	v_mbcnt_lo_u32_b32 v2, -1, 0
	v_lshlrev_b32_e32 v2, 8, v2
	v_add_u32_e32 v2, 0x6400, v2
	v_mov_b32_e32 v3, 1
	global_atomic_add v2, v3, s[6:7]
	s_mov_b64 exec, 0
	s_mov_b64 s[38:39], 0

; __device__ __forceinline__ unsigned xb_add(unsigned* p, unsigned v) { return __hip_atomic_fetch_add(p, v, __ATOMIC_RELAXED, __HIP_MEMORY_SCOPE_AGENT); }
; __device__ __forceinline__ void xcd_barrier(const XcdBarrier& b) {
;     ...
;             __builtin_amdgcn_fence(__ATOMIC_ACQUIRE, "agent");
;             xb_add(&bar[XB_XGEN(b.x)], 1u);
;             asm volatile("s_waitcnt vmcnt(0)" ::: "memory");
.LBB0_399:
	s_or_b64 exec, exec, s[6:7]
	s_mov_b64 s[6:7], exec
	v_mbcnt_lo_u32_b32 v0, s6, 0
	v_mbcnt_hi_u32_b32 v0, s7, v0
	v_cmp_eq_u32_e32 vcc, 0, v0
	s_waitcnt vmcnt(0)
	buffer_inv sc1
	s_and_saveexec_b64 s[12:13], vcc
	s_cbranch_execz .LBB0_401
	s_bcnt1_i32_b64 s2, s[6:7]
	v_mov_b32_e32 v0, s2
	v_mov_b32_e32 v2, 0x2000
.LBB0_401:
	s_or_b64 exec, exec, s[12:13]
	s_waitcnt vmcnt(0)

; __device__ __forceinline__ unsigned xb_ld(unsigned* p)              { return __hip_atomic_load(p, __ATOMIC_RELAXED, __HIP_MEMORY_SCOPE_AGENT); }
; __device__ __forceinline__ unsigned xb_add(unsigned* p, unsigned v) { return __hip_atomic_fetch_add(p, v, __ATOMIC_RELAXED, __HIP_MEMORY_SCOPE_AGENT); }
; #define XB_SPIN(cond, bar) do { unsigned _sp = 0; while (cond) { __builtin_amdgcn_s_sleep(1); \
;     if ((++_sp & 255u) == 0u) { if (xb_ld(&(bar)[XB_TMO])) break; if (_sp > XB_SPIN_CAP) { atomicAdd(&(bar)[XB_TMO], 1u); break; } } } } while (0)
; __device__ __forceinline__ void xcd_barrier(const XcdBarrier& b) {
;     ...
;         const unsigned old = xb_add(&bar[XB_XSUB(b.x)], 1u);
;         const unsigned gen = old / nloc;
;         if (old + 1u == (gen + 1u) * nloc) {
;             __builtin_amdgcn_fence(__ATOMIC_RELEASE, "agent");
;             asm volatile("s_waitcnt vmcnt(0)" ::: "memory");
;             const unsigned og = xb_add(&bar[XB_TOP], 1u);
;             const unsigned tg = og / nx;
;             if (og + 1u == (tg + 1u) * nx) xb_add(&bar[XB_TOPGEN], 1u);
;             else XB_SPIN(xb_ld(&bar[XB_TOPGEN]) == tg, bar);
;             __builtin_amdgcn_fence(__ATOMIC_ACQUIRE, "agent");
;             xb_add(&bar[XB_XGEN(b.x)], 1u);
;             asm volatile("s_waitcnt vmcnt(0)" ::: "memory");
;         } else {
;             XB_SPIN(xb_ld(&bar[XB_XGEN(b.x)]) == gen, bar);
.LBB0_499:
	s_or_b64 exec, exec, s[40:41]
	v_cvt_f32_u32_e32 v5, v3
	s_waitcnt vmcnt(0)
	v_readfirstlane_b32 s2, v4
	v_sub_u32_e32 v4, 0, v3
	v_rcp_iflag_f32_e32 v5, v5
	v_add_u32_e32 v6, s2, v2
	v_mul_f32_e32 v5, 0x4f7ffffe, v5
	v_cvt_u32_f32_e32 v5, v5
	v_mul_lo_u32 v2, v4, v5
	v_mul_hi_u32 v2, v5, v2
	v_add_u32_e32 v2, v5, v2
	v_mul_hi_u32 v2, v6, v2
	v_mul_lo_u32 v4, v2, v3
	v_sub_u32_e32 v4, v6, v4
	v_add_u32_e32 v5, 1, v2
	v_cmp_ge_u32_e32 vcc, v4, v3
	s_nop 1
	v_cndmask_b32_e32 v2, v2, v5, vcc
	v_sub_u32_e32 v5, v4, v3
	v_cndmask_b32_e32 v4, v4, v5, vcc
	v_add_u32_e32 v5, 1, v2
	v_cmp_ge_u32_e32 vcc, v4, v3
	v_add_u32_e32 v4, 1, v6
	s_nop 0
	v_cndmask_b32_e32 v2, v2, v5, vcc
	v_mul_lo_u32 v5, v3, v2
	v_add_u32_e32 v3, v5, v3
	v_cmp_ne_u32_e32 vcc, v4, v3
	v_mov_b32_e32 v17, v2
	s_and_saveexec_b64 s[14:15], vcc
	s_xor_b64 s[14:15], exec, s[14:15]
	s_cbranch_execz .LBB0_513
	s_waitcnt lgkmcnt(0)
	v_mov_b32_e32 v0, 0x2000
	global_load_dword v0, v0, s[12:13] offset:1024 sc1
	s_add_u32 s44, s12, 0x2400
	s_addc_u32 s45, s13, 0
	s_waitcnt vmcnt(0)
	v_cmp_eq_u32_e32 vcc, v0, v2
	s_and_saveexec_b64 s[40:41], vcc
	s_cbranch_execz .LBB0_512
	s_add_u32 s42, s8, 0x4200
	s_addc_u32 s43, s9, 0
	s_mov_b32 s2, 1
	s_mov_b64 s[46:47], 0
	s_branch .LBB0_503

; __device__ __forceinline__ unsigned xb_ld(unsigned* p)              { return __hip_atomic_load(p, __ATOMIC_RELAXED, __HIP_MEMORY_SCOPE_AGENT); }
; __device__ __forceinline__ unsigned xb_add(unsigned* p, unsigned v) { return __hip_atomic_fetch_add(p, v, __ATOMIC_RELAXED, __HIP_MEMORY_SCOPE_AGENT); }
; #define XB_SPIN(cond, bar) do { unsigned _sp = 0; while (cond) { __builtin_amdgcn_s_sleep(1); \
;     if ((++_sp & 255u) == 0u) { if (xb_ld(&(bar)[XB_TMO])) break; if (_sp > XB_SPIN_CAP) { atomicAdd(&(bar)[XB_TMO], 1u); break; } } } } while (0)
; __device__ __forceinline__ void xcd_barrier(const XcdBarrier& b) {
;     ...
;             const unsigned og = xb_add(&bar[XB_TOP], 1u);
;             const unsigned tg = og / nx;
;             if (og + 1u == (tg + 1u) * nx) xb_add(&bar[XB_TOPGEN], 1u);
;             else XB_SPIN(xb_ld(&bar[XB_TOPGEN]) == tg, bar);
.LBB0_516:
	s_or_b64 exec, exec, s[40:41]
	v_cvt_f32_u32_e32 v4, v0
	s_waitcnt vmcnt(0)
	v_readfirstlane_b32 s2, v3
	s_add_u32 s40, s12, 0x2400
	s_addc_u32 s41, s13, 0
	v_rcp_iflag_f32_e32 v4, v4
	v_add_u32_e32 v2, s2, v2
	v_add_u32_e32 v5, 1, v2
	s_mov_b64 s[42:43], -1
	v_mul_f32_e32 v3, 0x4f7ffffe, v4
	v_cvt_u32_f32_e32 v3, v3
	v_sub_u32_e32 v4, 0, v0
	v_mul_lo_u32 v4, v4, v3
	v_mul_hi_u32 v4, v3, v4
	v_add_u32_e32 v3, v3, v4
	v_mul_hi_u32 v3, v2, v3
	v_mul_lo_u32 v4, v3, v0
	v_sub_u32_e32 v2, v2, v4
	v_add_u32_e32 v6, 1, v3
	v_cmp_ge_u32_e32 vcc, v2, v0
	v_sub_u32_e32 v4, v2, v0
	s_nop 0
	v_cndmask_b32_e32 v3, v3, v6, vcc
	v_cndmask_b32_e32 v2, v2, v4, vcc
	v_add_u32_e32 v4, 1, v3
	v_cmp_ge_u32_e32 vcc, v2, v0
	s_nop 1
	v_cndmask_b32_e32 v4, v3, v4, vcc
	v_mul_lo_u32 v2, v0, v4
	v_add_u32_e32 v0, v2, v0
	v_cmp_ne_u32_e32 vcc, v5, v0
	v_mov_b64_e32 v[2:3], s[40:41]
	s_and_saveexec_b64 s[14:15], vcc
	s_cbranch_execz .Lxb2_last
	global_load_dword v0, v1, s[40:41] sc1
	s_mov_b64 s[46:47], 0
	s_waitcnt vmcnt(0)
	v_cmp_eq_u32_e32 vcc, v0, v17
	s_and_saveexec_b64 s[44:45], vcc
	s_cbranch_execz .LBB0_527
	s_add_u32 s42, s8, 0x4200
	s_addc_u32 s43, s9, 0
	s_mov_b32 s2, 1
	s_mov_b64 s[8:9], 0
	s_branch .LBB0_520

; __device__ __forceinline__ unsigned xb_ld(unsigned* p)              { return __hip_atomic_load(p, __ATOMIC_RELAXED, __HIP_MEMORY_SCOPE_AGENT); }
; __device__ __forceinline__ unsigned xb_add(unsigned* p, unsigned v) { return __hip_atomic_fetch_add(p, v, __ATOMIC_RELAXED, __HIP_MEMORY_SCOPE_AGENT); }
; #define XB_SPIN(cond, bar) do { unsigned _sp = 0; while (cond) { __builtin_amdgcn_s_sleep(1); \
;     if ((++_sp & 255u) == 0u) { if (xb_ld(&(bar)[XB_TMO])) break; if (_sp > XB_SPIN_CAP) { atomicAdd(&(bar)[XB_TMO], 1u); break; } } } } while (0)
; __device__ __forceinline__ void xcd_barrier(const XcdBarrier& b) {
;     ...
;             if (og + 1u == (tg + 1u) * nx) xb_add(&bar[XB_TOPGEN], 1u);
;             else XB_SPIN(xb_ld(&bar[XB_TOPGEN]) == tg, bar);
.LBB0_522:
	global_load_dword v0, v1, s[40:41] sc1
	s_add_i32 s2, s2, 1
	s_mov_b64 s[50:51], -1
	s_waitcnt vmcnt(0)
	v_cmp_ne_u32_e32 vcc, v0, v17
	s_orn2_b64 s[48:49], vcc, exec
	s_branch .LBB0_519

; __device__ __forceinline__ unsigned xb_ld(unsigned* p)              { return __hip_atomic_load(p, __ATOMIC_RELAXED, __HIP_MEMORY_SCOPE_AGENT); }
; __device__ __forceinline__ unsigned xb_add(unsigned* p, unsigned v) { return __hip_atomic_fetch_add(p, v, __ATOMIC_RELAXED, __HIP_MEMORY_SCOPE_AGENT); }
; #define XB_SPIN(cond, bar) do { unsigned _sp = 0; while (cond) { __builtin_amdgcn_s_sleep(1); \
;     if ((++_sp & 255u) == 0u) { if (xb_ld(&(bar)[XB_TMO])) break; if (_sp > XB_SPIN_CAP) { atomicAdd(&(bar)[XB_TMO], 1u); break; } } } } while (0)
; __device__ __forceinline__ void xcd_barrier(const XcdBarrier& b) {
;     ...
;             const unsigned og = xb_add(&bar[XB_TOP], 1u);
;             const unsigned tg = og / nx;
;             if (og + 1u == (tg + 1u) * nx) xb_add(&bar[XB_TOPGEN], 1u);
;             else XB_SPIN(xb_ld(&bar[XB_TOPGEN]) == tg, bar);
;             __builtin_amdgcn_fence(__ATOMIC_ACQUIRE, "agent");
;             xb_add(&bar[XB_XGEN(b.x)], 1u);
.LBB0_527:
	s_or_b64 exec, exec, s[44:45]
	v_mov_b64_e32 v[2:3], s[42:43]
	s_orn2_b64 s[42:43], s[46:47], exec
	s_branch .LBB0_528
.Lxb2_last:
	s_mov_b64 exec, 0xffff
	v_mbcnt_lo_u32_b32 v2, -1, 0
	v_lshlrev_b32_e32 v2, 8, v2
	v_add_u32_e32 v2, 0x6400, v2
	v_mov_b32_e32 v3, 1
	global_atomic_add v2, v3, s[8:9]
	s_mov_b64 exec, 0
	s_mov_b64 s[42:43], 0

; __device__ __forceinline__ unsigned xb_add(unsigned* p, unsigned v) { return __hip_atomic_fetch_add(p, v, __ATOMIC_RELAXED, __HIP_MEMORY_SCOPE_AGENT); }
; __device__ __forceinline__ void xcd_barrier(const XcdBarrier& b) {
;     ...
;             __builtin_amdgcn_fence(__ATOMIC_ACQUIRE, "agent");
;             xb_add(&bar[XB_XGEN(b.x)], 1u);
;             asm volatile("s_waitcnt vmcnt(0)" ::: "memory");
.LBB0_530:
	s_or_b64 exec, exec, s[8:9]
	s_mov_b64 s[8:9], exec
	v_mbcnt_lo_u32_b32 v0, s8, 0
	v_mbcnt_hi_u32_b32 v0, s9, v0
	v_cmp_eq_u32_e32 vcc, 0, v0
	s_waitcnt vmcnt(0)
	buffer_inv sc1
	s_and_saveexec_b64 s[14:15], vcc
	s_cbranch_execz .LBB0_532
	s_bcnt1_i32_b64 s2, s[8:9]
	v_mov_b32_e32 v0, s2
	v_mov_b32_e32 v2, 0x2000
.LBB0_532:
	s_or_b64 exec, exec, s[14:15]
	s_waitcnt vmcnt(0)

; __device__ __forceinline__ unsigned xb_ld(unsigned* p)              { return __hip_atomic_load(p, __ATOMIC_RELAXED, __HIP_MEMORY_SCOPE_AGENT); }
; __device__ __forceinline__ unsigned xb_add(unsigned* p, unsigned v) { return __hip_atomic_fetch_add(p, v, __ATOMIC_RELAXED, __HIP_MEMORY_SCOPE_AGENT); }
; #define XB_SPIN(cond, bar) do { unsigned _sp = 0; while (cond) { __builtin_amdgcn_s_sleep(1); \
;     if ((++_sp & 255u) == 0u) { if (xb_ld(&(bar)[XB_TMO])) break; if (_sp > XB_SPIN_CAP) { atomicAdd(&(bar)[XB_TMO], 1u); break; } } } } while (0)
; __device__ __forceinline__ void xcd_barrier(const XcdBarrier& b) {
;     ...
;         const unsigned old = xb_add(&bar[XB_XSUB(b.x)], 1u);
;         const unsigned gen = old / nloc;
;         if (old + 1u == (gen + 1u) * nloc) {
;             __builtin_amdgcn_fence(__ATOMIC_RELEASE, "agent");
;             asm volatile("s_waitcnt vmcnt(0)" ::: "memory");
;             const unsigned og = xb_add(&bar[XB_TOP], 1u);
;             const unsigned tg = og / nx;
;             if (og + 1u == (tg + 1u) * nx) xb_add(&bar[XB_TOPGEN], 1u);
;             else XB_SPIN(xb_ld(&bar[XB_TOPGEN]) == tg, bar);
;             __builtin_amdgcn_fence(__ATOMIC_ACQUIRE, "agent");
;             xb_add(&bar[XB_XGEN(b.x)], 1u);
;             asm volatile("s_waitcnt vmcnt(0)" ::: "memory");
;         } else {
;             XB_SPIN(xb_ld(&bar[XB_XGEN(b.x)]) == gen, bar);
.LBB0_723:
	s_or_b64 exec, exec, s[38:39]
	v_cvt_f32_u32_e32 v5, v3
	s_waitcnt vmcnt(0)
	v_readfirstlane_b32 s2, v4
	v_sub_u32_e32 v4, 0, v3
	v_rcp_iflag_f32_e32 v5, v5
	v_add_u32_e32 v6, s2, v2
	v_mul_f32_e32 v5, 0x4f7ffffe, v5
	v_cvt_u32_f32_e32 v5, v5
	v_mul_lo_u32 v2, v4, v5
	v_mul_hi_u32 v2, v5, v2
	v_add_u32_e32 v2, v5, v2
	v_mul_hi_u32 v2, v6, v2
	v_mul_lo_u32 v4, v2, v3
	v_sub_u32_e32 v4, v6, v4
	v_add_u32_e32 v5, 1, v2
	v_cmp_ge_u32_e32 vcc, v4, v3
	s_nop 1
	v_cndmask_b32_e32 v2, v2, v5, vcc
	v_sub_u32_e32 v5, v4, v3
	v_cndmask_b32_e32 v4, v4, v5, vcc
	v_add_u32_e32 v5, 1, v2
	v_cmp_ge_u32_e32 vcc, v4, v3
	v_add_u32_e32 v4, 1, v6
	s_nop 0
	v_cndmask_b32_e32 v2, v2, v5, vcc
	v_mul_lo_u32 v5, v3, v2
	v_add_u32_e32 v3, v5, v3
	v_cmp_ne_u32_e32 vcc, v4, v3
	v_mov_b32_e32 v17, v2
	s_and_saveexec_b64 s[14:15], vcc
	s_xor_b64 s[14:15], exec, s[14:15]
	s_cbranch_execz .LBB0_737
	s_waitcnt lgkmcnt(0)
	v_mov_b32_e32 v0, 0x2000
	global_load_dword v0, v0, s[12:13] offset:1024 sc1
	s_add_u32 s42, s12, 0x2400
	s_addc_u32 s43, s13, 0
	s_waitcnt vmcnt(0)
	v_cmp_eq_u32_e32 vcc, v0, v2
	s_and_saveexec_b64 s[38:39], vcc
	s_cbranch_execz .LBB0_736
	s_add_u32 s40, s8, 0x4200
	s_addc_u32 s41, s9, 0
	s_mov_b32 s2, 1
	s_mov_b64 s[44:45], 0
	s_branch .LBB0_727

; __device__ __forceinline__ unsigned xb_ld(unsigned* p)              { return __hip_atomic_load(p, __ATOMIC_RELAXED, __HIP_MEMORY_SCOPE_AGENT); }
; __device__ __forceinline__ unsigned xb_add(unsigned* p, unsigned v) { return __hip_atomic_fetch_add(p, v, __ATOMIC_RELAXED, __HIP_MEMORY_SCOPE_AGENT); }
; #define XB_SPIN(cond, bar) do { unsigned _sp = 0; while (cond) { __builtin_amdgcn_s_sleep(1); \
;     if ((++_sp & 255u) == 0u) { if (xb_ld(&(bar)[XB_TMO])) break; if (_sp > XB_SPIN_CAP) { atomicAdd(&(bar)[XB_TMO], 1u); break; } } } } while (0)
; __device__ __forceinline__ void xcd_barrier(const XcdBarrier& b) {
;     ...
;             const unsigned og = xb_add(&bar[XB_TOP], 1u);
;             const unsigned tg = og / nx;
;             if (og + 1u == (tg + 1u) * nx) xb_add(&bar[XB_TOPGEN], 1u);
;             else XB_SPIN(xb_ld(&bar[XB_TOPGEN]) == tg, bar);
.LBB0_740:
	s_or_b64 exec, exec, s[38:39]
	v_cvt_f32_u32_e32 v4, v0
	s_waitcnt vmcnt(0)
	v_readfirstlane_b32 s2, v3
	s_add_u32 s38, s12, 0x2400
	s_addc_u32 s39, s13, 0
	v_rcp_iflag_f32_e32 v4, v4
	v_add_u32_e32 v2, s2, v2
	v_add_u32_e32 v5, 1, v2
	s_mov_b64 s[40:41], -1
	v_mul_f32_e32 v3, 0x4f7ffffe, v4
	v_cvt_u32_f32_e32 v3, v3
	v_sub_u32_e32 v4, 0, v0
	v_mul_lo_u32 v4, v4, v3
	v_mul_hi_u32 v4, v3, v4
	v_add_u32_e32 v3, v3, v4
	v_mul_hi_u32 v3, v2, v3
	v_mul_lo_u32 v4, v3, v0
	v_sub_u32_e32 v2, v2, v4
	v_add_u32_e32 v6, 1, v3
	v_cmp_ge_u32_e32 vcc, v2, v0
	v_sub_u32_e32 v4, v2, v0
	s_nop 0
	v_cndmask_b32_e32 v3, v3, v6, vcc
	v_cndmask_b32_e32 v2, v2, v4, vcc
	v_add_u32_e32 v4, 1, v3
	v_cmp_ge_u32_e32 vcc, v2, v0
	s_nop 1
	v_cndmask_b32_e32 v4, v3, v4, vcc
	v_mul_lo_u32 v2, v0, v4
	v_add_u32_e32 v0, v2, v0
	v_cmp_ne_u32_e32 vcc, v5, v0
	v_mov_b64_e32 v[2:3], s[38:39]
	s_and_saveexec_b64 s[14:15], vcc
	s_cbranch_execz .Lxb3_last
	global_load_dword v0, v1, s[38:39] sc1
	s_mov_b64 s[44:45], 0
	s_waitcnt vmcnt(0)
	v_cmp_eq_u32_e32 vcc, v0, v17
	s_and_saveexec_b64 s[42:43], vcc
	s_cbranch_execz .LBB0_751
	s_add_u32 s40, s8, 0x4200
	s_addc_u32 s41, s9, 0
	s_mov_b32 s2, 1
	s_mov_b64 s[8:9], 0
	s_branch .LBB0_744

; __device__ __forceinline__ unsigned xb_ld(unsigned* p)              { return __hip_atomic_load(p, __ATOMIC_RELAXED, __HIP_MEMORY_SCOPE_AGENT); }
; __device__ __forceinline__ unsigned xb_add(unsigned* p, unsigned v) { return __hip_atomic_fetch_add(p, v, __ATOMIC_RELAXED, __HIP_MEMORY_SCOPE_AGENT); }
; #define XB_SPIN(cond, bar) do { unsigned _sp = 0; while (cond) { __builtin_amdgcn_s_sleep(1); \
;     if ((++_sp & 255u) == 0u) { if (xb_ld(&(bar)[XB_TMO])) break; if (_sp > XB_SPIN_CAP) { atomicAdd(&(bar)[XB_TMO], 1u); break; } } } } while (0)
; __device__ __forceinline__ void xcd_barrier(const XcdBarrier& b) {
;     ...
;             if (og + 1u == (tg + 1u) * nx) xb_add(&bar[XB_TOPGEN], 1u);
;             else XB_SPIN(xb_ld(&bar[XB_TOPGEN]) == tg, bar);
.LBB0_746:
	global_load_dword v0, v1, s[38:39] sc1
	s_add_i32 s2, s2, 1
	s_mov_b64 s[48:49], -1
	s_waitcnt vmcnt(0)
	v_cmp_ne_u32_e32 vcc, v0, v17
	s_orn2_b64 s[46:47], vcc, exec
	s_branch .LBB0_743

; __device__ __forceinline__ unsigned xb_ld(unsigned* p)              { return __hip_atomic_load(p, __ATOMIC_RELAXED, __HIP_MEMORY_SCOPE_AGENT); }
; __device__ __forceinline__ unsigned xb_add(unsigned* p, unsigned v) { return __hip_atomic_fetch_add(p, v, __ATOMIC_RELAXED, __HIP_MEMORY_SCOPE_AGENT); }
; #define XB_SPIN(cond, bar) do { unsigned _sp = 0; while (cond) { __builtin_amdgcn_s_sleep(1); \
;     if ((++_sp & 255u) == 0u) { if (xb_ld(&(bar)[XB_TMO])) break; if (_sp > XB_SPIN_CAP) { atomicAdd(&(bar)[XB_TMO], 1u); break; } } } } while (0)
; __device__ __forceinline__ void xcd_barrier(const XcdBarrier& b) {
;     ...
;             const unsigned og = xb_add(&bar[XB_TOP], 1u);
;             const unsigned tg = og / nx;
;             if (og + 1u == (tg + 1u) * nx) xb_add(&bar[XB_TOPGEN], 1u);
;             else XB_SPIN(xb_ld(&bar[XB_TOPGEN]) == tg, bar);
;             __builtin_amdgcn_fence(__ATOMIC_ACQUIRE, "agent");
;             xb_add(&bar[XB_XGEN(b.x)], 1u);
.LBB0_751:
	s_or_b64 exec, exec, s[42:43]
	v_mov_b64_e32 v[2:3], s[40:41]
	s_orn2_b64 s[40:41], s[44:45], exec
	s_branch .LBB0_752
.Lxb3_last:
	s_mov_b64 exec, 0xffff
	v_mbcnt_lo_u32_b32 v2, -1, 0
	v_lshlrev_b32_e32 v2, 8, v2
	v_add_u32_e32 v2, 0x6400, v2
	v_mov_b32_e32 v3, 1
	global_atomic_add v2, v3, s[8:9]
	s_mov_b64 exec, 0
	s_mov_b64 s[40:41], 0

; __device__ __forceinline__ unsigned xb_add(unsigned* p, unsigned v) { return __hip_atomic_fetch_add(p, v, __ATOMIC_RELAXED, __HIP_MEMORY_SCOPE_AGENT); }
; __device__ __forceinline__ void xcd_barrier(const XcdBarrier& b) {
;     ...
;             __builtin_amdgcn_fence(__ATOMIC_ACQUIRE, "agent");
;             xb_add(&bar[XB_XGEN(b.x)], 1u);
;             asm volatile("s_waitcnt vmcnt(0)" ::: "memory");
.LBB0_754:
	s_or_b64 exec, exec, s[8:9]
	s_mov_b64 s[8:9], exec
	v_mbcnt_lo_u32_b32 v0, s8, 0
	v_mbcnt_hi_u32_b32 v0, s9, v0
	v_cmp_eq_u32_e32 vcc, 0, v0
	s_waitcnt vmcnt(0)
	buffer_inv sc1
	s_and_saveexec_b64 s[14:15], vcc
	s_cbranch_execz .LBB0_756
	s_bcnt1_i32_b64 s2, s[8:9]
	v_mov_b32_e32 v0, s2
	v_mov_b32_e32 v2, 0x2000
.LBB0_756:
	s_or_b64 exec, exec, s[14:15]
	s_waitcnt vmcnt(0)

; __device__ __forceinline__ unsigned xb_add(unsigned* p, unsigned v) { return __hip_atomic_fetch_add(p, v, __ATOMIC_RELAXED, __HIP_MEMORY_SCOPE_AGENT); }
; __device__ __forceinline__ void xcd_barrier(const XcdBarrier& b) {
;     ...
;             __builtin_amdgcn_fence(__ATOMIC_ACQUIRE, "agent");
;             xb_add(&bar[XB_XGEN(b.x)], 1u);
;             asm volatile("s_waitcnt vmcnt(0)" ::: "memory");
.LBB0_930:
	s_or_b64 exec, exec, s[8:9]
	s_mov_b64 s[8:9], exec
	v_mbcnt_lo_u32_b32 v0, s8, 0
	v_mbcnt_hi_u32_b32 v0, s9, v0
	v_cmp_eq_u32_e32 vcc, 0, v0
	s_waitcnt vmcnt(0)
	buffer_inv sc1
	s_and_saveexec_b64 s[14:15], vcc
	s_cbranch_execz .LBB0_932
	s_bcnt1_i32_b64 s2, s[8:9]
	v_mov_b32_e32 v0, s2
	v_mov_b32_e32 v2, 0x2000
.LBB0_932:
	s_or_b64 exec, exec, s[14:15]
	s_waitcnt vmcnt(0)

; __device__ __forceinline__ unsigned xb_ld(unsigned* p)              { return __hip_atomic_load(p, __ATOMIC_RELAXED, __HIP_MEMORY_SCOPE_AGENT); }
; __device__ __forceinline__ unsigned xb_add(unsigned* p, unsigned v) { return __hip_atomic_fetch_add(p, v, __ATOMIC_RELAXED, __HIP_MEMORY_SCOPE_AGENT); }
; #define XB_SPIN(cond, bar) do { unsigned _sp = 0; while (cond) { __builtin_amdgcn_s_sleep(1); \
;     if ((++_sp & 255u) == 0u) { if (xb_ld(&(bar)[XB_TMO])) break; if (_sp > XB_SPIN_CAP) { atomicAdd(&(bar)[XB_TMO], 1u); break; } } } } while (0)
; __device__ __forceinline__ void xcd_barrier(const XcdBarrier& b) {
;     ...
;         const unsigned old = xb_add(&bar[XB_XSUB(b.x)], 1u);
;         const unsigned gen = old / nloc;
;         if (old + 1u == (gen + 1u) * nloc) {
;             __builtin_amdgcn_fence(__ATOMIC_RELEASE, "agent");
;             asm volatile("s_waitcnt vmcnt(0)" ::: "memory");
;             const unsigned og = xb_add(&bar[XB_TOP], 1u);
;             const unsigned tg = og / nx;
;             if (og + 1u == (tg + 1u) * nx) xb_add(&bar[XB_TOPGEN], 1u);
;             else XB_SPIN(xb_ld(&bar[XB_TOPGEN]) == tg, bar);
;             __builtin_amdgcn_fence(__ATOMIC_ACQUIRE, "agent");
;             xb_add(&bar[XB_XGEN(b.x)], 1u);
;             asm volatile("s_waitcnt vmcnt(0)" ::: "memory");
;         } else {
;             XB_SPIN(xb_ld(&bar[XB_XGEN(b.x)]) == gen, bar);
.LBB0_992:
	s_or_b64 exec, exec, s[10:11]
	v_cvt_f32_u32_e32 v4, v2
	s_waitcnt vmcnt(0)
	v_readfirstlane_b32 s8, v3
	v_sub_u32_e32 v3, 0, v2
	v_rcp_iflag_f32_e32 v4, v4
	v_add_u32_e32 v5, s8, v1
	v_mul_f32_e32 v4, 0x4f7ffffe, v4
	v_cvt_u32_f32_e32 v4, v4
	v_mul_lo_u32 v1, v3, v4
	v_mul_hi_u32 v1, v4, v1
	v_add_u32_e32 v1, v4, v1
	v_mul_hi_u32 v1, v5, v1
	v_mul_lo_u32 v3, v1, v2
	v_sub_u32_e32 v3, v5, v3
	v_add_u32_e32 v4, 1, v1
	v_cmp_ge_u32_e32 vcc, v3, v2
	s_nop 1
	v_cndmask_b32_e32 v1, v1, v4, vcc
	v_sub_u32_e32 v4, v3, v2
	v_cndmask_b32_e32 v3, v3, v4, vcc
	v_add_u32_e32 v4, 1, v1
	v_cmp_ge_u32_e32 vcc, v3, v2
	v_add_u32_e32 v3, 1, v5
	s_nop 0
	v_cndmask_b32_e32 v1, v1, v4, vcc
	v_mul_lo_u32 v4, v2, v1
	v_add_u32_e32 v2, v4, v2
	v_cmp_ne_u32_e32 vcc, v3, v2
	v_mov_b32_e32 v17, v1
	s_and_saveexec_b64 s[8:9], vcc
	s_xor_b64 s[8:9], exec, s[8:9]
	s_cbranch_execz .LBB0_1006
	s_waitcnt lgkmcnt(0)
	v_mov_b32_e32 v0, 0x2000
	global_load_dword v0, v0, s[6:7] offset:1024 sc1
	s_add_u32 s14, s6, 0x2400
	s_addc_u32 s15, s7, 0
	s_waitcnt vmcnt(0)
	v_cmp_eq_u32_e32 vcc, v0, v1
	s_and_saveexec_b64 s[10:11], vcc
	s_cbranch_execz .LBB0_1005
	s_add_u32 s12, s4, 0x4200
	s_addc_u32 s13, s5, 0
	s_mov_b32 s26, 1
	s_mov_b64 s[16:17], 0
	v_mov_b32_e32 v0, 0
	s_branch .LBB0_996

; __device__ __forceinline__ unsigned xb_ld(unsigned* p)              { return __hip_atomic_load(p, __ATOMIC_RELAXED, __HIP_MEMORY_SCOPE_AGENT); }
; __device__ __forceinline__ unsigned xb_add(unsigned* p, unsigned v) { return __hip_atomic_fetch_add(p, v, __ATOMIC_RELAXED, __HIP_MEMORY_SCOPE_AGENT); }
; #define XB_SPIN(cond, bar) do { unsigned _sp = 0; while (cond) { __builtin_amdgcn_s_sleep(1); \
;     if ((++_sp & 255u) == 0u) { if (xb_ld(&(bar)[XB_TMO])) break; if (_sp > XB_SPIN_CAP) { atomicAdd(&(bar)[XB_TMO], 1u); break; } } } } while (0)
; __device__ __forceinline__ void xcd_barrier(const XcdBarrier& b) {
;     ...
;             const unsigned og = xb_add(&bar[XB_TOP], 1u);
;             const unsigned tg = og / nx;
;             if (og + 1u == (tg + 1u) * nx) xb_add(&bar[XB_TOPGEN], 1u);
;             else XB_SPIN(xb_ld(&bar[XB_TOPGEN]) == tg, bar);
.LBB0_1009:
	s_or_b64 exec, exec, s[10:11]
	v_cvt_f32_u32_e32 v3, v0
	s_waitcnt vmcnt(0)
	v_readfirstlane_b32 s8, v2
	s_add_u32 s10, s6, 0x2400
	s_addc_u32 s11, s7, 0
	v_rcp_iflag_f32_e32 v3, v3
	v_add_u32_e32 v1, s8, v1
	v_add_u32_e32 v4, 1, v1
	s_mov_b64 s[12:13], -1
	v_mul_f32_e32 v2, 0x4f7ffffe, v3
	v_cvt_u32_f32_e32 v2, v2
	v_sub_u32_e32 v3, 0, v0
	v_mul_lo_u32 v3, v3, v2
	v_mul_hi_u32 v3, v2, v3
	v_add_u32_e32 v2, v2, v3
	v_mul_hi_u32 v2, v1, v2
	v_mul_lo_u32 v3, v2, v0
	v_sub_u32_e32 v1, v1, v3
	v_add_u32_e32 v5, 1, v2
	v_cmp_ge_u32_e32 vcc, v1, v0
	v_sub_u32_e32 v3, v1, v0
	s_nop 0
	v_cndmask_b32_e32 v2, v2, v5, vcc
	v_cndmask_b32_e32 v1, v1, v3, vcc
	v_add_u32_e32 v3, 1, v2
	v_cmp_ge_u32_e32 vcc, v1, v0
	s_nop 1
	v_cndmask_b32_e32 v2, v2, v3, vcc
	v_mul_lo_u32 v1, v0, v2
	v_add_u32_e32 v0, v1, v0
	v_cmp_ne_u32_e32 vcc, v4, v0
	v_mov_b64_e32 v[0:1], s[10:11]
	s_and_saveexec_b64 s[8:9], vcc
	s_cbranch_execz .Lxb5_last
	v_mov_b32_e32 v0, 0
	global_load_dword v1, v0, s[10:11] sc1
	s_mov_b64 s[16:17], 0
	s_waitcnt vmcnt(0)
	v_cmp_eq_u32_e32 vcc, v1, v17
	s_and_saveexec_b64 s[14:15], vcc
	s_cbranch_execz .LBB0_1020
	s_add_u32 s12, s4, 0x4200
	s_addc_u32 s13, s5, 0
	s_mov_b32 s24, 1
	s_mov_b64 s[4:5], 0
	s_branch .LBB0_1013

; __device__ __forceinline__ unsigned xb_ld(unsigned* p)              { return __hip_atomic_load(p, __ATOMIC_RELAXED, __HIP_MEMORY_SCOPE_AGENT); }
; __device__ __forceinline__ unsigned xb_add(unsigned* p, unsigned v) { return __hip_atomic_fetch_add(p, v, __ATOMIC_RELAXED, __HIP_MEMORY_SCOPE_AGENT); }
; #define XB_SPIN(cond, bar) do { unsigned _sp = 0; while (cond) { __builtin_amdgcn_s_sleep(1); \
;     if ((++_sp & 255u) == 0u) { if (xb_ld(&(bar)[XB_TMO])) break; if (_sp > XB_SPIN_CAP) { atomicAdd(&(bar)[XB_TMO], 1u); break; } } } } while (0)
; __device__ __forceinline__ void xcd_barrier(const XcdBarrier& b) {
;     ...
;             if (og + 1u == (tg + 1u) * nx) xb_add(&bar[XB_TOPGEN], 1u);
;             else XB_SPIN(xb_ld(&bar[XB_TOPGEN]) == tg, bar);
.LBB0_1015:
	global_load_dword v1, v0, s[10:11] sc1
	s_add_i32 s24, s24, 1
	s_mov_b64 s[18:19], -1
	s_waitcnt vmcnt(0)
	v_cmp_ne_u32_e32 vcc, v1, v17
	s_orn2_b64 s[22:23], vcc, exec
	s_branch .LBB0_1012

; __device__ __forceinline__ unsigned xb_ld(unsigned* p)              { return __hip_atomic_load(p, __ATOMIC_RELAXED, __HIP_MEMORY_SCOPE_AGENT); }
; __device__ __forceinline__ unsigned xb_add(unsigned* p, unsigned v) { return __hip_atomic_fetch_add(p, v, __ATOMIC_RELAXED, __HIP_MEMORY_SCOPE_AGENT); }
; #define XB_SPIN(cond, bar) do { unsigned _sp = 0; while (cond) { __builtin_amdgcn_s_sleep(1); \
;     if ((++_sp & 255u) == 0u) { if (xb_ld(&(bar)[XB_TMO])) break; if (_sp > XB_SPIN_CAP) { atomicAdd(&(bar)[XB_TMO], 1u); break; } } } } while (0)
; __device__ __forceinline__ void xcd_barrier(const XcdBarrier& b) {
;     ...
;             const unsigned og = xb_add(&bar[XB_TOP], 1u);
;             const unsigned tg = og / nx;
;             if (og + 1u == (tg + 1u) * nx) xb_add(&bar[XB_TOPGEN], 1u);
;             else XB_SPIN(xb_ld(&bar[XB_TOPGEN]) == tg, bar);
;             __builtin_amdgcn_fence(__ATOMIC_ACQUIRE, "agent");
;             xb_add(&bar[XB_XGEN(b.x)], 1u);
.LBB0_1020:
	s_or_b64 exec, exec, s[14:15]
	v_mov_b64_e32 v[0:1], s[12:13]
	s_orn2_b64 s[12:13], s[16:17], exec
	s_branch .LBB0_1021
.Lxb5_last:
	s_mov_b64 exec, 0xffff
	v_mbcnt_lo_u32_b32 v2, -1, 0
	v_lshlrev_b32_e32 v2, 8, v2
	v_add_u32_e32 v2, 0x6400, v2
	v_mov_b32_e32 v3, 1
	global_atomic_add v2, v3, s[4:5]
	s_mov_b64 exec, 0
	s_mov_b64 s[12:13], 0

; __device__ __forceinline__ unsigned xb_add(unsigned* p, unsigned v) { return __hip_atomic_fetch_add(p, v, __ATOMIC_RELAXED, __HIP_MEMORY_SCOPE_AGENT); }
; __device__ __forceinline__ void xcd_barrier(const XcdBarrier& b) {
;     ...
;             __builtin_amdgcn_fence(__ATOMIC_ACQUIRE, "agent");
;             xb_add(&bar[XB_XGEN(b.x)], 1u);
;             asm volatile("s_waitcnt vmcnt(0)" ::: "memory");
.LBB0_1023:
	s_or_b64 exec, exec, s[4:5]
	s_mov_b64 s[4:5], exec
	v_mbcnt_lo_u32_b32 v0, s4, 0
	v_mbcnt_hi_u32_b32 v0, s5, v0
	v_cmp_eq_u32_e32 vcc, 0, v0
	s_waitcnt vmcnt(0)
	buffer_inv sc1
	s_and_saveexec_b64 s[8:9], vcc
	s_cbranch_execz .LBB0_1025
	s_bcnt1_i32_b64 s4, s[4:5]
	v_mov_b32_e32 v0, 0x2000
	v_mov_b32_e32 v1, s4
.LBB0_1025:
	s_or_b64 exec, exec, s[8:9]
	s_waitcnt vmcnt(0)
